# v38_attn_next_unit_prefetch
# speedup vs baseline: 1.0349x; 1.0014x over previous
; __device__ __forceinline__ KArgs kargs() { KArgs p = (KArgs)__builtin_amdgcn_kernarg_segment_ptr(); asm volatile("" : "+s"(p)); return p; }
; #define X make_ctx(lds_raw)
;     ...
;     const int per = (1536 + (int)gridDim.x - 1) / (int)gridDim.x, u0 = (int)blockIdx.x * per, u1 = (u0 + per < 1536) ? u0 + per : 1536;
;     int cur_half = 1;
;     for (int unit = u0; unit < u1; ++unit) {
; __global__ void __launch_bounds__(512, 2) fwd_megakernel(Args a_kernarg) {
;     ...
;     for (int step = 0; step < 2; ++step) {
;         if (((step ^ (int)blockIdx.x) & 1) == 0) { KArgs a = kargs(); gla_a1(X, a, a->out, WSP(float, WS_SSQ)); }
;         else attn_mfma(X, kargs());
;         __syncthreads();
;     }
.LBB0_328:
	s_cmp_lg_u32 s0, s23
	s_mov_b64 s[0:1], -1
	s_cbranch_scc0 .LBB0_337
	v_writelane_b32 v254, s26, 43
	v_mov_b32_e32 v0, v186
	s_nop 0
	v_writelane_b32 v254, s27, 44
	v_readfirstlane_b32 s2, v0
	v_readlane_b32 s6, v254, 53
	v_readlane_b32 s7, v254, 54
	s_and_b64 vcc, exec, s[6:7]
	s_cbranch_vccnz .LBB0_336
; #define LAS __attribute__((address_space(3)))
; #define X make_ctx(lds_raw)
;     ...
;     const int fr = X.lane & 15, fq = X.lane >> 4, w = X.wave, i0 = 16 * w;
;     const int per = (1536 + (int)gridDim.x - 1) / (int)gridDim.x, u0 = (int)blockIdx.x * per, u1 = (u0 + per < 1536) ? u0 + per : 1536;
;     int cur_half = 1;
;     for (int unit = u0; unit < u1; ++unit) {
;         const int b = unit / 384, rem = unit % 384, h = rem >> 5, pn = rem & 31, g = h >> 2, hg = h & 3;
;         const int r = (g == 0) ? 1 : (g == 1 ? 4 : 16), nblk = 32 / r, p = pn / nblk, n = pn % nblk;
;         const int tb = b * SEQ + p;
;         const bool reuse = (unit > u0) && (n >= 1);
;         if (reuse) cur_half ^= 1;
;         const int prev_half = cur_half ^ 1;
;         __syncthreads();
;         { const int i = X.tid >> 2, c = X.tid & 3; const int t = tb + (128 * n + i) * r; const bf16_t* src = proj + (size_t)t * NMAIN + C_AQ + h * 64 + 16 * c;
;           *(LAS u32x4*)(Qs + i * QP + 16 * c) = *(const u32x4*)src; *(LAS u32x4*)(Qs + i * QP + 16 * c + 8) = *(const u32x4*)(src + 8); }
;         for (int blk = reuse ? 1 : 0; blk < 2; ++blk) {
;             const int half = blk ? cur_half : prev_half;
;             { const int j = X.tid >> 2, c = X.tid & 3; int m = 128 * (n - 1 + blk) + j; m = m < 0 ? 0 : m; const int t = tb + m * r;
;               const bf16_t* src = proj + (size_t)t * NMAIN + C_AK + h * 64 + 16 * c;
;               *(LAS u32x4*)(Ks + (half * 128 + j) * QP + 16 * c) = *(const u32x4*)src; *(LAS u32x4*)(Ks + (half * 128 + j) * QP + 16 * c + 8) = *(const u32x4*)(src + 8); }
; #pragma unroll
;             for (int q = 0; q < 2; ++q) { const int idx = X.tid + 512 * q, j = idx & 127, c = idx >> 7; int m = 128 * (n - 1 + blk) + j; m = m < 0 ? 0 : m; const int t = tb + m * r;
;                 const u32x4 wv = *(const u32x4*)(proj + (size_t)t * NMAIN + C_AV + h * 64 + 8 * c);
;                 LAS bf16_t* vp = Vt + (8 * c) * VP + half * 128 + j;
;                 vp[0 * VP] = (bf16_t)(wv.x & 0xffff); vp[1 * VP] = (bf16_t)(wv.x >> 16); vp[2 * VP] = (bf16_t)(wv.y & 0xffff); vp[3 * VP] = (bf16_t)(wv.y >> 16);
;                 vp[4 * VP] = (bf16_t)(wv.z & 0xffff); vp[5 * VP] = (bf16_t)(wv.z >> 16); vp[6 * VP] = (bf16_t)(wv.w & 0xffff); vp[7 * VP] = (bf16_t)(wv.w >> 16); }
	s_load_dwordx2 s[0:1], s[86:87], 0xa0
	v_and_b32_e32 v16, 15, v0
	v_and_b32_e32 v1, 63, v0
	v_bfe_u32 v6, v0, 4, 2
	v_cmp_gt_u32_e64 s[6:7], 16, v1
	s_waitcnt lgkmcnt(0)
	s_add_u32 s48, s0, 0x4f00000
	s_addc_u32 s49, s1, 0
	s_add_u32 s5, s0, 0x200000
	s_addc_u32 s33, s1, 0
	s_ashr_i32 s0, s2, 6
	s_lshl_b32 s1, s0, 4
	s_cmp_lt_u32 s0, 8
	v_or_b32_e32 v5, s1, v16
	s_cselect_b64 s[50:51], -1, 0
	s_and_b32 s2, s1, 0x70
	s_add_i32 s1, s0, 1
	s_cmp_lt_u32 s1, 8
	s_cselect_b64 s[52:53], -1, 0
	s_lshl_b32 s1, s1, 4
	s_and_b32 s3, s1, 0x70
	s_add_i32 s1, s0, 2
	s_cmp_lt_u32 s1, 8
	s_cselect_b64 s[54:55], -1, 0
	s_lshl_b32 s8, s1, 4
	s_and_b32 s24, s8, 0x70
	s_add_i32 s8, s0, 3
	s_cmp_lt_u32 s8, 8
	s_cselect_b64 s[56:57], -1, 0
	s_lshl_b32 s8, s8, 4
	s_and_b32 s25, s8, 0x70
	s_add_i32 s26, s0, 4
	s_cmp_lt_u32 s26, 8
	s_cselect_b64 s[58:59], -1, 0
	s_lshl_b32 s8, s26, 4
	s_and_b32 s27, s8, 0x70
	s_add_i32 s8, s0, 5
	s_cmp_lt_u32 s8, 8
	s_cselect_b64 s[60:61], -1, 0
	s_lshl_b32 s8, s8, 4
	s_and_b32 s38, s8, 0x70
	s_add_i32 s41, s0, 6
	s_cmp_lt_u32 s41, 8
	s_cselect_b64 s[62:63], -1, 0
	s_lshl_b32 s8, s41, 4
	s_and_b32 s42, s8, 0x70
	s_add_i32 s8, s0, 7
	s_cmp_lt_u32 s8, 8
	s_cselect_b64 s[64:65], -1, 0
	s_lshl_b32 s8, s8, 4
	s_and_b32 s43, s8, 0x70
	s_cmp_gt_u32 s0, -9
	s_cselect_b64 s[66:67], -1, 0
	s_cmp_gt_i32 s0, 7
	s_cselect_b64 s[68:69], -1, 0
	s_cmp_gt_i32 s0, 6
	s_cselect_b64 s[70:71], -1, 0
	s_cmp_gt_i32 s0, 5
	s_cselect_b64 s[72:73], -1, 0
	s_cmp_gt_i32 s0, 4
	s_cselect_b64 s[74:75], -1, 0
	s_cmp_gt_i32 s0, 3
	s_cselect_b64 s[76:77], -1, 0
	s_cmp_gt_i32 s0, 2
	s_cselect_b64 s[78:79], -1, 0
	s_cmp_gt_i32 s0, 1
	s_cselect_b64 s[80:81], -1, 0
	s_cmp_gt_i32 s0, 0
	s_cselect_b64 s[82:83], -1, 0
	s_cmp_gt_i32 s0, -1
	s_cselect_b64 s[84:85], -1, 0
	s_min_i32 s44, s0, 14
	s_add_i32 s44, s44, 1
	s_cmp_lt_u32 s44, 8
	s_cselect_b64 s[86:87], -1, 0
	s_lshl_b32 s44, s44, 5
	s_min_i32 s1, s1, 14
	v_mul_lo_u32 v2, v5, s34
	s_lshl_b32 s45, s2, 1
	s_and_b32 s44, s44, 0xe0
	s_add_i32 s1, s1, 1
	v_add_u32_e32 v17, 0, v2
	v_lshlrev_b32_e32 v2, 2, v6
	v_lshlrev_b32_e32 v6, 3, v6
	v_mul_u32_u24_e32 v1, 0x210, v16
	s_cmp_lt_u32 s1, 8
	v_add3_u32 v1, 0, v6, v1
	s_cselect_b64 s[88:89], -1, 0
	s_lshl_b32 s1, s1, 5
	v_add_u32_e32 v6, 0xd800, v1
	s_and_b32 s1, s1, 0xe0
	v_add_u32_e32 v24, s1, v1
	v_add_u32_e32 v26, s1, v6
	s_min_i32 s1, s26, 14
	v_add_u32_e32 v20, s44, v1
	v_add_u32_e32 v22, s44, v6
	s_lshl_b32 s44, s24, 1
	s_add_i32 s1, s1, 1
	s_cmp_lt_u32 s1, 8
	s_cselect_b64 s[90:91], -1, 0
	s_lshl_b32 s1, s1, 5
	s_and_b32 s1, s1, 0xe0
	v_add_u32_e32 v28, s1, v1
	v_add_u32_e32 v32, s1, v6
	s_min_i32 s1, s41, 14
	s_lshl_b32 s26, s27, 1
	s_add_i32 s1, s1, 1
	s_cmp_lt_u32 s1, 8
	s_cselect_b64 s[92:93], -1, 0
	s_lshl_b32 s1, s1, 5
	s_min_i32 s0, s0, 6
	v_add_u32_e32 v27, s26, v1
	v_add_u32_e32 v29, s26, v6
	s_lshl_b32 s26, s42, 1
	s_and_b32 s1, s1, 0xe0
	s_add_i32 s0, s0, 9
	s_cmp_lt_u32 s0, 8
	s_cselect_b64 s[94:95], -1, 0
	s_lshl_b32 s0, s0, 5
	s_and_b32 s0, s0, 0xe0
	v_cmp_lt_i32_e32 vcc, v143, v190
	v_add_u32_e32 v19, s45, v1
	v_add_u32_e32 v23, s44, v1
	v_add_u32_e32 v33, s26, v1
	v_add_u32_e32 v34, s1, v1
	v_add_u32_e32 v37, s0, v1
	v_lshlrev_b32_e32 v1, 4, v0
	v_sub_u32_e32 v8, v16, v2
	v_cndmask_b32_e32 v7, v187, v143, vcc
	v_cmp_lt_i32_e32 vcc, v142, v190
	v_add_u32_e32 v21, s45, v6
	v_add_u32_e32 v25, s44, v6
	v_add_u32_e32 v35, s26, v6
	v_add_u32_e32 v36, s1, v6
	v_add_u32_e32 v38, s0, v6
	v_and_b32_e32 v6, 48, v1
	v_cndmask_b32_e32 v10, v187, v142, vcc
	v_cmp_gt_i32_e64 s[8:9], 1, v8
	v_cmp_gt_i32_e64 s[10:11], 2, v8
	v_cmp_gt_i32_e64 s[12:13], 3, v8
	v_cmp_gt_i32_e64 s[14:15], 4, v8
	v_cmp_lt_i32_e64 s[16:17], -1, v8
	v_cmp_lt_i32_e64 s[18:19], 0, v8
	v_cmp_lt_i32_e64 s[20:21], 1, v8
	v_cmp_lt_i32_e64 s[22:23], 2, v8
	v_ashrrev_i32_e32 v39, 2, v0
	v_lshl_add_u32 v8, v6, 1, 0
	v_lshlrev_b32_e32 v18, 2, v10
	v_mad_u64_u32 v[10:11], s[0:1], v39, s34, v[8:9]
	v_and_b32_e32 v51, 48, v0
	v_and_b32_e32 v11, 0x7f, v0
	v_ashrrev_i32_e32 v1, 4, v0
	v_add_u32_e32 v0, 0x200, v0
	v_ashrrev_i32_e32 v0, 4, v0
	v_and_b32_e32 v12, -8, v1
	s_movk_i32 s0, 0x210
	v_and_b32_e32 v14, -8, v0
	v_add_u32_e32 v4, 0, v51
	v_lshlrev_b32_e32 v7, 2, v7
	s_mov_b32 s40, 1
	v_lshl_add_u32 v40, v11, 1, 0
	v_ashrrev_i32_e32 v13, 31, v12
	v_mul_lo_u32 v41, v12, s0
	v_ashrrev_i32_e32 v15, 31, v14
	v_mul_lo_u32 v42, v14, s0
	v_or_b32_e32 v43, s2, v16
	v_or_b32_e32 v44, s3, v16
	v_or_b32_e32 v45, s24, v16
	v_or_b32_e32 v46, s25, v16
	v_or_b32_e32 v47, s27, v16
	v_or_b32_e32 v48, s38, v16
	v_or_b32_e32 v49, s42, v16
	v_or_b32_e32 v50, s43, v16
	v_add_u32_e32 v51, v17, v51
	v_lshlrev_b32_e32 v16, 1, v2
	s_mov_b32 s98, s30
	s_mul_hi_i32 s24, s98, 0x2aaaaaab
	s_lshr_b32 s25, s24, 31
	s_ashr_i32 s24, s24, 6
	s_add_i32 s24, s24, s25
	s_mul_i32 s25, s24, 0xfffffe80
	s_add_i32 s98, s98, s25
	s_and_b32 s25, s98, 31
	s_ashr_i32 s26, s98, 7
	s_cmp_eq_u32 s26, 1
	s_cselect_b32 s26, 2, 4
	s_cmpk_gt_u32 s98, 0x7f
	s_cselect_b32 s99, s26, 0
	s_lshr_b32 s26, 32, s99
	s_sub_i32 s27, 5, s99
	s_lshr_b32 s27, s25, s27
	s_add_i32 s26, s26, -1
	s_lshl_b32 s24, s24, 12
	s_and_b32 s26, s26, s25
	s_or_b32 s100, s27, s24
	s_lshl_b32 s24, s98, 1
	s_andn2_b32 s24, s24, 63
	s_lshl_b32 s101, s24, 1
	s_lshl_b32 s24, s26, 7
	s_add_i32 s25, s26, -1
	s_lshl_b32 s27, s25, 7
	s_cmp_gt_i32 s25, -1
	s_cselect_b64 vcc, -1, 0
	v_add_u32_e32 v134, s24, v39
	v_add_u32_e32 v135, s27, v39
	v_or_b32_e32 v144, s27, v11
	v_max_i32_e32 v135, 0, v135
	v_cndmask_b32_e32 v144, 0, v144, vcc
	v_lshlrev_b32_e32 v134, s99, v134
	v_lshlrev_b32_e32 v135, s99, v135
	v_lshlrev_b32_e32 v144, s99, v144
	v_add_u32_e32 v134, s100, v134
	v_add_u32_e32 v135, s100, v135
	v_add_u32_e32 v144, s100, v144
	v_mov_b64_e32 v[136:137], s[48:49]
	v_mad_i64_i32 v[138:139], s[24:25], v134, s35, v[136:137]
	v_mad_i64_i32 v[146:147], s[24:25], v135, s35, v[136:137]
	v_mad_i64_i32 v[150:151], s[24:25], v144, s35, v[136:137]
	v_lshl_add_u32 v140, v6, 1, s101
	v_mov_b32_e32 v141, 0
	v_mov_b32_e32 v135, 0
	v_add_u32_e32 v134, 0x1800, v140
	v_add_u32_e32 v140, 0x1e00, v140
	v_lshl_add_u64 v[138:139], v[138:139], 0, v[134:135]
	v_lshl_add_u64 v[146:147], v[146:147], 0, v[140:141]
	v_lshl_add_u32 v134, v12, 1, s101
	v_lshl_add_u32 v140, v14, 1, s101
	v_add_u32_e32 v134, 0x2400, v134
	v_add_u32_e32 v140, 0x2400, v140
	v_lshl_add_u64 v[148:149], v[150:151], 0, v[134:135]
	v_lshl_add_u64 v[150:151], v[150:151], 0, v[140:141]
	global_load_dwordx4 v[110:113], v[138:139], off
	global_load_dwordx4 v[114:117], v[138:139], off offset:16
	global_load_dwordx4 v[118:121], v[146:147], off
	global_load_dwordx4 v[122:125], v[146:147], off offset:16
	global_load_dwordx4 v[126:129], v[148:149], off
	global_load_dwordx4 v[130:133], v[150:151], off
	s_mov_b32 s41, s30
	s_branch .LBB0_332

; #define LAS __attribute__((address_space(3)))
; #define X make_ctx(lds_raw)
;     ...
;         const int b = unit / 384, rem = unit % 384, h = rem >> 5, pn = rem & 31, g = h >> 2, hg = h & 3;
;         const int r = (g == 0) ? 1 : (g == 1 ? 4 : 16), nblk = 32 / r, p = pn / nblk, n = pn % nblk;
;         const int tb = b * SEQ + p;
;         const bool reuse = (unit > u0) && (n >= 1);
;         if (reuse) cur_half ^= 1;
;         const int prev_half = cur_half ^ 1;
;         __syncthreads();
;         { const int i = X.tid >> 2, c = X.tid & 3; const int t = tb + (128 * n + i) * r; const bf16_t* src = proj + (size_t)t * NMAIN + C_AQ + h * 64 + 16 * c;
;           *(LAS u32x4*)(Qs + i * QP + 16 * c) = *(const u32x4*)src; *(LAS u32x4*)(Qs + i * QP + 16 * c + 8) = *(const u32x4*)(src + 8); }
;         for (int blk = reuse ? 1 : 0; blk < 2; ++blk) {
;             const int half = blk ? cur_half : prev_half;
;             { const int j = X.tid >> 2, c = X.tid & 3; int m = 128 * (n - 1 + blk) + j; m = m < 0 ? 0 : m; const int t = tb + m * r;
;               const bf16_t* src = proj + (size_t)t * NMAIN + C_AK + h * 64 + 16 * c;
;               *(LAS u32x4*)(Ks + (half * 128 + j) * QP + 16 * c) = *(const u32x4*)src; *(LAS u32x4*)(Ks + (half * 128 + j) * QP + 16 * c + 8) = *(const u32x4*)(src + 8); }
; #pragma unroll
;             for (int q = 0; q < 2; ++q) { const int idx = X.tid + 512 * q, j = idx & 127, c = idx >> 7; int m = 128 * (n - 1 + blk) + j; m = m < 0 ? 0 : m; const int t = tb + m * r;
;                 const u32x4 wv = *(const u32x4*)(proj + (size_t)t * NMAIN + C_AV + h * 64 + 8 * c);
;                 LAS bf16_t* vp = Vt + (8 * c) * VP + half * 128 + j;
;                 vp[0 * VP] = (bf16_t)(wv.x & 0xffff); vp[1 * VP] = (bf16_t)(wv.x >> 16); vp[2 * VP] = (bf16_t)(wv.y & 0xffff); vp[3 * VP] = (bf16_t)(wv.y >> 16);
;                 vp[4 * VP] = (bf16_t)(wv.z & 0xffff); vp[5 * VP] = (bf16_t)(wv.z >> 16); vp[6 * VP] = (bf16_t)(wv.w & 0xffff); vp[7 * VP] = (bf16_t)(wv.w >> 16); }
;         }
;         __syncthreads();
;     ...
;         bf16x8 bq[2];
; #pragma unroll
;         for (int ks = 0; ks < 2; ++ks) bq[ks] = *(const LAS bf16x8*)(Qs + (i0 + fr) * QP + 32 * ks + 8 * fq);
;         f32x4 sc[9];
; #pragma unroll
;         for (int q = 0; q < 9; ++q) { sc[q] = (f32x4){0.f, 0.f, 0.f, 0.f};
; #pragma unroll
.LBB0_332:
	s_mul_hi_i32 s0, s41, 0x2aaaaaab
	s_lshr_b32 s1, s0, 31
	s_ashr_i32 s0, s0, 6
	s_add_i32 s0, s0, s1
	s_mul_i32 s1, s0, 0xfffffe80
	s_add_i32 s38, s41, s1
	s_and_b32 s1, s38, 31
	s_ashr_i32 s96, s38, 7
	s_cmp_eq_u32 s96, 1
	s_cselect_b32 s2, 2, 4
	s_cmpk_gt_u32 s38, 0x7f
	s_cselect_b32 s97, s2, 0
	s_lshr_b32 s2, 32, s97
	s_sub_i32 s3, 5, s97
	s_lshr_b32 s3, s1, s3
	s_add_i32 s2, s2, -1
	s_lshl_b32 s0, s0, 12
	s_and_b32 s26, s2, s1
	s_or_b32 s44, s3, s0
	s_cmp_gt_i32 s41, s30
	s_cselect_b64 s[0:1], -1, 0
	v_add_co_u32_e64 v0, s[2:3], s26, -1
	s_and_b64 s[42:43], s[0:1], s[2:3]
	v_cndmask_b32_e64 v1, 0, 1, s[42:43]
	s_lshl_b32 s45, s26, 7
	v_readfirstlane_b32 s0, v1
	s_xor_b32 s40, s40, s0
	s_lshl_b32 s0, s38, 1
	s_andn2_b32 s0, s0, 63
	s_ashr_i32 s1, s0, 31
	s_xor_b32 s46, s40, 1
	s_lshl_b64 s[24:25], s[0:1], 1
	s_and_b64 vcc, s[42:43], exec
	s_cselect_b32 s27, s40, s46
	v_add_u32_e32 v0, s45, v39
	v_lshlrev_b32_e32 v2, 1, v6
	s_nop 0
	s_nop 0
	s_barrier
	s_cmp_lg_u32 s41, s30
	s_cbranch_scc1 .Lapf_steady
	s_waitcnt vmcnt(0)
.Lapf_steady:
	s_waitcnt vmcnt(5)
	v_cmp_ne_u32_e32 vcc, 1, v1
	v_lshl_add_u32 v1, s27, 7, v39
	v_lshl_add_u32 v17, s27, 8, v40
	v_mad_u64_u32 v[76:77], s[42:43], v1, s34, v[8:9]
	v_add_u32_e32 v1, v17, v41
	v_add_u32_e32 v17, v17, v42
	s_and_b64 vcc, exec, vcc
	ds_write_b128 v10, v[110:113]
	ds_write_b128 v10, v[114:117] offset:16
	ds_write_b128 v76, v[118:121] offset:18432
	ds_write_b128 v76, v[122:125] offset:18448
	ds_write_b16 v1, v126 offset:55296
	ds_write_b16_d16_hi v1, v126 offset:55824
	ds_write_b16 v1, v127 offset:56352
	ds_write_b16_d16_hi v1, v127 offset:56880
	ds_write_b16 v1, v128 offset:57408
	ds_write_b16_d16_hi v1, v128 offset:57936
	ds_write_b16 v1, v129 offset:58464
	ds_write_b16_d16_hi v1, v129 offset:58992
	ds_write_b16 v17, v130 offset:55296
	ds_write_b16_d16_hi v17, v130 offset:55824
	ds_write_b16 v17, v131 offset:56352
	ds_write_b16_d16_hi v17, v131 offset:56880
	ds_write_b16 v17, v132 offset:57408
	ds_write_b16_d16_hi v17, v132 offset:57936
	ds_write_b16 v17, v133 offset:58464
	ds_write_b16_d16_hi v17, v133 offset:58992
	s_cbranch_vccz .LBB0_334
	v_max_i32_e32 v0, 0, v0
	v_lshlrev_b32_e32 v0, s97, v0
	v_add_u32_e32 v17, s44, v0
	v_mov_b64_e32 v[0:1], s[48:49]
	v_mad_i64_i32 v[52:53], s[26:27], v17, s35, v[0:1]
	v_lshl_add_u64 v[52:53], v[52:53], 0, s[24:25]
	v_lshl_add_u64 v[52:53], v[52:53], 0, v[2:3]
	v_or_b32_e32 v2, s45, v11
	v_lshlrev_b32_e32 v2, s97, v2
	s_mov_b64 s[26:27], 0x1e00
	v_add_u32_e32 v2, s44, v2
	v_lshl_add_u64 v[56:57], v[52:53], 0, s[26:27]
	v_add_co_u32_e32 v52, vcc, 0x1000, v52
	v_mad_i64_i32 v[0:1], s[26:27], v2, s35, v[0:1]
	s_nop 0
	v_addc_co_u32_e32 v53, vcc, 0, v53, vcc
	v_lshl_add_u64 v[0:1], v[0:1], 0, s[24:25]
	s_mov_b64 s[24:25], 0x2400
	global_load_dwordx4 v[52:55], v[52:53], off offset:3584
	s_nop 0
	global_load_dwordx4 v[56:59], v[56:57], off offset:16
	v_lshl_add_u64 v[0:1], v[0:1], 0, s[24:25]
	v_lshl_add_u64 v[60:61], v[12:13], 1, v[0:1]
	global_load_dwordx4 v[60:63], v[60:61], off
	v_lshl_add_u64 v[0:1], v[14:15], 1, v[0:1]
	global_load_dwordx4 v[64:67], v[0:1], off
	v_lshl_add_u32 v0, s40, 7, v39
	v_lshl_add_u32 v2, s40, 8, v40
	v_mad_u64_u32 v[0:1], s[24:25], v0, s34, v[8:9]
	v_add_u32_e32 v1, v2, v41
	v_add_u32_e32 v2, v2, v42
	s_waitcnt vmcnt(3)
	ds_write_b128 v0, v[52:55] offset:18432
	s_waitcnt vmcnt(2)
	ds_write_b128 v0, v[56:59] offset:18448
	s_waitcnt vmcnt(1)
	ds_write_b16 v1, v60 offset:55296
	ds_write_b16_d16_hi v1, v60 offset:55824
	ds_write_b16 v1, v61 offset:56352
	ds_write_b16_d16_hi v1, v61 offset:56880
	ds_write_b16 v1, v62 offset:57408
	ds_write_b16_d16_hi v1, v62 offset:57936
	ds_write_b16 v1, v63 offset:58464
	ds_write_b16_d16_hi v1, v63 offset:58992
	s_waitcnt vmcnt(0)
	ds_write_b16 v2, v64 offset:55296
	ds_write_b16_d16_hi v2, v64 offset:55824
	ds_write_b16 v2, v65 offset:56352
	ds_write_b16_d16_hi v2, v65 offset:56880
	ds_write_b16 v2, v66 offset:57408
	ds_write_b16_d16_hi v2, v66 offset:57936
	ds_write_b16 v2, v67 offset:58464
	ds_write_b16_d16_hi v2, v67 offset:58992
.LBB0_334:
	s_and_b64 s[24:25], s[50:51], exec
	s_cselect_b32 s43, s46, s40
	v_lshl_or_b32 v0, s43, 7, v43
	v_mad_u64_u32 v[0:1], s[24:25], v0, s34, v[4:5]
	s_waitcnt lgkmcnt(0)
	s_barrier
	ds_read_b128 v[52:55], v0 offset:18432
	ds_read_b128 v[56:59], v0 offset:18496
	ds_read_b128 v[60:63], v51
	ds_read_b128 v[64:67], v51 offset:64
	v_readlane_b32 s24, v254, 41
	s_add_i32 s98, s41, 1
	s_cmp_lt_i32 s98, s24
	s_cbranch_scc0 .Lapf_skip
	s_mul_hi_i32 s24, s98, 0x2aaaaaab
	s_lshr_b32 s25, s24, 31
	s_ashr_i32 s24, s24, 6
	s_add_i32 s24, s24, s25
	s_mul_i32 s25, s24, 0xfffffe80
	s_add_i32 s98, s98, s25
	s_and_b32 s25, s98, 31
	s_ashr_i32 s26, s98, 7
	s_cmp_eq_u32 s26, 1
	s_cselect_b32 s26, 2, 4
	s_cmpk_gt_u32 s98, 0x7f
	s_cselect_b32 s99, s26, 0
	s_lshr_b32 s26, 32, s99
	s_sub_i32 s27, 5, s99
	s_lshr_b32 s27, s25, s27
	s_add_i32 s26, s26, -1
	s_lshl_b32 s24, s24, 12
	s_and_b32 s26, s26, s25
	s_or_b32 s100, s27, s24
	s_lshl_b32 s24, s98, 1
	s_andn2_b32 s24, s24, 63
	s_lshl_b32 s101, s24, 1
	s_lshl_b32 s24, s26, 7
	s_cmp_gt_u32 s26, 0
	s_cselect_b32 s25, s26, -1
	s_lshl_b32 s27, s25, 7
	s_cmp_gt_i32 s25, -1
	s_cselect_b64 vcc, -1, 0
	v_add_u32_e32 v134, s24, v39
	v_add_u32_e32 v135, s27, v39
	v_or_b32_e32 v144, s27, v11
	v_max_i32_e32 v135, 0, v135
	v_cndmask_b32_e32 v144, 0, v144, vcc
	v_lshlrev_b32_e32 v134, s99, v134
	v_lshlrev_b32_e32 v135, s99, v135
	v_lshlrev_b32_e32 v144, s99, v144
	v_add_u32_e32 v134, s100, v134
	v_add_u32_e32 v135, s100, v135
	v_add_u32_e32 v144, s100, v144
	v_mov_b64_e32 v[136:137], s[48:49]
	v_mad_i64_i32 v[138:139], s[24:25], v134, s35, v[136:137]
	v_mad_i64_i32 v[146:147], s[24:25], v135, s35, v[136:137]
	v_mad_i64_i32 v[150:151], s[24:25], v144, s35, v[136:137]
	v_lshl_add_u32 v140, v6, 1, s101
	v_mov_b32_e32 v141, 0
	v_mov_b32_e32 v135, 0
	v_add_u32_e32 v134, 0x1800, v140
	v_add_u32_e32 v140, 0x1e00, v140
	v_lshl_add_u64 v[138:139], v[138:139], 0, v[134:135]
	v_lshl_add_u64 v[146:147], v[146:147], 0, v[140:141]
	v_lshl_add_u32 v134, v12, 1, s101
	v_lshl_add_u32 v140, v14, 1, s101
	v_add_u32_e32 v134, 0x2400, v134
	v_add_u32_e32 v140, 0x2400, v140
	v_lshl_add_u64 v[148:149], v[150:151], 0, v[134:135]
	v_lshl_add_u64 v[150:151], v[150:151], 0, v[140:141]
	global_load_dwordx4 v[110:113], v[138:139], off
	global_load_dwordx4 v[114:117], v[138:139], off offset:16
	global_load_dwordx4 v[118:121], v[146:147], off
	global_load_dwordx4 v[122:125], v[146:147], off offset:16
	global_load_dwordx4 v[126:129], v[148:149], off
	global_load_dwordx4 v[130:133], v[150:151], off
; #define LAS __attribute__((address_space(3)))
;     ...
;         for (int ks = 0; ks < 2; ++ks) bq[ks] = *(const LAS bf16x8*)(Qs + (i0 + fr) * QP + 32 * ks + 8 * fq);
;         f32x4 sc[9];
; #pragma unroll
;         for (int q = 0; q < 9; ++q) { sc[q] = (f32x4){0.f, 0.f, 0.f, 0.f};
; #pragma unroll
;             for (int ks = 0; ks < 2; ++ks) { const bf16x8 ak = *(const LAS bf16x8*)(Ks + (KOFF(w + q) + fr) * QP + 32 * ks + 8 * fq); sc[q] = __builtin_amdgcn_mfma_f32_16x16x32_bf16(ak, bq[ks], sc[q], 0, 0, 0); } }
;         const int iq = i0 + fr;
;         float mx = -INFINITY;
; #pragma unroll
;         for (int q = 0; q < 9; ++q) { const bool tile_ok = (n > 0) || (w + q >= 8);
; #pragma unroll
;             for (int e = 0; e < 4; ++e) { bool valid = tile_ok;
;                 if (q == 0) valid = valid && (4 * fq + e >= fr);
;                 if (q == 8) valid = valid && (4 * fq + e <= fr);
;                 sc[q][e] = valid ? sc[q][e] : -INFINITY; mx = fmaxf(mx, sc[q][e]); } }
;         mx = fmaxf(mx, __shfl_xor(mx, 16)); mx = fmaxf(mx, __shfl_xor(mx, 32));
.Lapf_skip:
	s_waitcnt lgkmcnt(1)
	v_mfma_f32_16x16x32_bf16 v[52:55], v[52:55], v[60:63], 0
	s_and_b64 s[24:25], s[52:53], exec
	s_cselect_b32 s24, s46, s40
	v_lshl_or_b32 v0, s24, 7, v44
	v_mad_u64_u32 v[0:1], s[24:25], v0, s34, v[4:5]
	s_waitcnt lgkmcnt(0)
	v_mfma_f32_16x16x32_bf16 v[52:55], v[56:59], v[64:67], v[52:55]
	ds_read_b128 v[56:59], v0 offset:18432
	ds_read_b128 v[68:71], v0 offset:18496
	s_and_b64 s[24:25], s[54:55], exec
	s_cselect_b32 s42, s46, s40
	v_lshl_or_b32 v0, s42, 7, v45
	v_mad_u64_u32 v[0:1], s[24:25], v0, s34, v[4:5]
	s_waitcnt lgkmcnt(1)
	v_mfma_f32_16x16x32_bf16 v[56:59], v[56:59], v[60:63], 0
	ds_read_b128 v[72:75], v0 offset:18432
	s_and_b64 s[24:25], s[56:57], exec
	s_cselect_b32 s24, s46, s40
	s_waitcnt lgkmcnt(1)
	v_mfma_f32_16x16x32_bf16 v[56:59], v[68:71], v[64:67], v[56:59]
	ds_read_b128 v[68:71], v0 offset:18496
	v_lshl_or_b32 v0, s24, 7, v46
	v_mad_u64_u32 v[0:1], s[24:25], v0, s34, v[4:5]
	s_waitcnt lgkmcnt(1)
	v_mfma_f32_16x16x32_bf16 v[72:75], v[72:75], v[60:63], 0
	s_and_b64 s[24:25], s[58:59], exec
	s_cselect_b32 s47, s46, s40
	s_and_b64 s[24:25], s[60:61], exec
	s_waitcnt lgkmcnt(0)
	v_mfma_f32_16x16x32_bf16 v[68:71], v[68:71], v[64:67], v[72:75]
	s_nop 2
	ds_read_b128 v[72:75], v0 offset:18432
	ds_read_b128 v[76:79], v0 offset:18496
	v_lshl_or_b32 v0, s47, 7, v47
	v_mad_u64_u32 v[0:1], s[24:25], v0, s34, v[4:5]
	s_waitcnt lgkmcnt(1)
	v_mfma_f32_16x16x32_bf16 v[72:75], v[72:75], v[60:63], 0
	ds_read_b128 v[80:83], v0 offset:18432
	s_cselect_b32 s24, s46, s40
	s_waitcnt lgkmcnt(1)
	v_mfma_f32_16x16x32_bf16 v[72:75], v[76:79], v[64:67], v[72:75]
	ds_read_b128 v[76:79], v0 offset:18496
	v_lshl_or_b32 v0, s24, 7, v48
	v_mad_u64_u32 v[0:1], s[24:25], v0, s34, v[4:5]
	s_waitcnt lgkmcnt(1)
	v_mfma_f32_16x16x32_bf16 v[80:83], v[80:83], v[60:63], 0
	s_and_b64 s[24:25], s[62:63], exec
	s_cselect_b32 s25, s46, s40
	s_and_b64 vcc, s[64:65], exec
	s_waitcnt lgkmcnt(0)
	v_mfma_f32_16x16x32_bf16 v[76:79], v[76:79], v[64:67], v[80:83]
	s_nop 2
	ds_read_b128 v[80:83], v0 offset:18432
	ds_read_b128 v[84:87], v0 offset:18496
	v_lshl_or_b32 v0, s25, 7, v49
	v_mad_u64_u32 v[0:1], vcc, v0, s34, v[4:5]
	s_waitcnt lgkmcnt(1)
	v_mfma_f32_16x16x32_bf16 v[80:83], v[80:83], v[60:63], 0
	ds_read_b128 v[88:91], v0 offset:18432
	s_cselect_b32 s24, s46, s40
	s_and_b64 vcc, s[66:67], exec
	s_waitcnt lgkmcnt(1)
	v_mfma_f32_16x16x32_bf16 v[80:83], v[84:87], v[64:67], v[80:83]
	ds_read_b128 v[84:87], v0 offset:18496
	v_lshl_or_b32 v0, s24, 7, v50
	v_mad_u64_u32 v[0:1], vcc, v0, s34, v[4:5]
	s_waitcnt lgkmcnt(1)
	v_mfma_f32_16x16x32_bf16 v[88:91], v[88:91], v[60:63], 0
	s_cselect_b32 s24, s46, s40
	s_or_b64 s[26:27], s[2:3], s[68:69]
	s_waitcnt lgkmcnt(0)
	v_mfma_f32_16x16x32_bf16 v[84:87], v[84:87], v[64:67], v[88:91]
	s_nop 3
	ds_read_b128 v[88:91], v0 offset:18432
	ds_read_b128 v[92:95], v0 offset:18496
	v_lshl_or_b32 v0, s24, 7, v43
	v_mad_u64_u32 v[0:1], vcc, v0, s34, v[4:5]
	s_waitcnt lgkmcnt(1)
	v_mfma_f32_16x16x32_bf16 v[88:91], v[88:91], v[60:63], 0
	ds_read_b128 v[96:99], v0 offset:18432
	s_and_b64 vcc, s[26:27], s[8:9]
	s_waitcnt lgkmcnt(1)
	v_mfma_f32_16x16x32_bf16 v[88:91], v[92:95], v[64:67], v[88:91]
	ds_read_b128 v[92:95], v0 offset:18496
	s_waitcnt lgkmcnt(1)
	v_mfma_f32_16x16x32_bf16 v[60:63], v[96:99], v[60:63], 0
	s_waitcnt lgkmcnt(0)
	v_mfma_f32_16x16x32_bf16 v[60:63], v[92:95], v[64:67], v[60:63]
	v_cndmask_b32_e32 v64, v9, v52, vcc
	s_and_b64 vcc, s[26:27], s[10:11]
	v_cndmask_b32_e32 v65, v9, v53, vcc
	s_and_b64 vcc, s[26:27], s[12:13]
	v_cndmask_b32_e32 v54, v9, v54, vcc
	s_and_b64 vcc, s[26:27], s[14:15]
	v_max3_f32 v0, v64, s28, v65
	v_cndmask_b32_e32 v55, v9, v55, vcc
	s_or_b64 vcc, s[2:3], s[70:71]
	v_max3_f32 v0, v0, v54, v55
	v_cndmask_b32_e32 v56, v9, v56, vcc
	v_cndmask_b32_e32 v57, v9, v57, vcc
	v_max3_f32 v0, v0, v56, v57
	v_cndmask_b32_e32 v58, v9, v58, vcc
	v_cndmask_b32_e32 v59, v9, v59, vcc
	s_or_b64 vcc, s[2:3], s[72:73]
	v_max3_f32 v0, v0, v58, v59
	v_cndmask_b32_e32 v66, v9, v68, vcc
	v_cndmask_b32_e32 v67, v9, v69, vcc
	v_max3_f32 v0, v0, v66, v67
	v_cndmask_b32_e32 v68, v9, v70, vcc
	v_cndmask_b32_e32 v69, v9, v71, vcc
	s_or_b64 vcc, s[2:3], s[74:75]
	v_max3_f32 v0, v0, v68, v69
	v_cndmask_b32_e32 v70, v9, v72, vcc
	v_cndmask_b32_e32 v71, v9, v73, vcc
	v_max3_f32 v0, v0, v70, v71
	v_cndmask_b32_e32 v72, v9, v74, vcc
	v_cndmask_b32_e32 v73, v9, v75, vcc
	s_or_b64 vcc, s[2:3], s[76:77]
	v_max3_f32 v0, v0, v72, v73
	v_cndmask_b32_e32 v74, v9, v76, vcc
	v_cndmask_b32_e32 v75, v9, v77, vcc
	v_max3_f32 v0, v0, v74, v75
	v_cndmask_b32_e32 v76, v9, v78, vcc
	v_cndmask_b32_e32 v77, v9, v79, vcc
	s_or_b64 vcc, s[2:3], s[78:79]
	v_max3_f32 v0, v0, v76, v77
	v_cndmask_b32_e32 v78, v9, v80, vcc
	v_cndmask_b32_e32 v79, v9, v81, vcc
	v_max3_f32 v0, v0, v78, v79
	v_cndmask_b32_e32 v80, v9, v82, vcc
	v_cndmask_b32_e32 v81, v9, v83, vcc
	s_or_b64 vcc, s[2:3], s[80:81]
	v_max3_f32 v0, v0, v80, v81
	v_cndmask_b32_e32 v82, v9, v84, vcc
	v_cndmask_b32_e32 v83, v9, v85, vcc
	v_cndmask_b32_e32 v84, v9, v86, vcc
	v_cndmask_b32_e32 v85, v9, v87, vcc
	s_or_b64 vcc, s[2:3], s[82:83]
	s_or_b64 s[2:3], s[2:3], s[84:85]
	v_max3_f32 v0, v0, v82, v83
	v_cndmask_b32_e32 v86, v9, v88, vcc
	v_cndmask_b32_e32 v87, v9, v89, vcc
	v_cndmask_b32_e32 v88, v9, v90, vcc
	v_cndmask_b32_e32 v17, v9, v91, vcc
	s_and_b64 vcc, s[2:3], s[16:17]
	v_max3_f32 v0, v0, v84, v85
	v_cndmask_b32_e32 v53, v9, v60, vcc
	s_and_b64 vcc, s[2:3], s[18:19]
	v_max3_f32 v0, v0, v86, v87
	v_cndmask_b32_e32 v1, v9, v61, vcc
	s_and_b64 vcc, s[2:3], s[20:21]
	v_max3_f32 v0, v0, v88, v17
	v_cndmask_b32_e32 v2, v9, v62, vcc
	s_and_b64 vcc, s[2:3], s[22:23]
	v_max3_f32 v52, v0, v53, v1
	v_cndmask_b32_e32 v0, v9, v63, vcc
	v_max3_f32 v52, v52, v2, v0
	ds_bpermute_b32 v60, v7, v52
	s_lshl_b32 s26, s43, 8
	s_and_b64 s[2:3], s[86:87], exec
	s_cselect_b32 s2, s46, s40
	s_lshl_b32 s2, s2, 8
	s_waitcnt lgkmcnt(0)
; #define LAS __attribute__((address_space(3)))
; __device__ __forceinline__ unsigned pk2(float lo, float hi) { const f32x2 v = {lo, hi}; return __builtin_bit_cast(unsigned, __builtin_convertvector(v, bf16x2_hw)); }
;     ...
;         mx = fmaxf(mx, __shfl_xor(mx, 16)); mx = fmaxf(mx, __shfl_xor(mx, 32));
;         float l = 0.f;
; #pragma unroll
;         for (int q = 0; q < 9; ++q)
; #pragma unroll
;             for (int e = 0; e < 4; ++e) { sc[q][e] = __builtin_amdgcn_exp2f(sc[q][e] - mx); l += sc[q][e]; }
;         l += __shfl_xor(l, 16); l += __shfl_xor(l, 32);
;         f32x4 o[4];
; #pragma unroll
;         for (int dt = 0; dt < 4; ++dt) o[dt] = (f32x4){0.f, 0.f, 0.f, 0.f};
; #pragma unroll
;         for (int c = 0; c < 5; ++c) { const int jtA = w + 2 * c; int jtB = w + 2 * c + 1; jtB = jtB > 15 ? 15 : jtB;
;             const f32x4 pa = sc[2 * c]; const f32x4 pb = (2 * c + 1 <= 8) ? sc[(2 * c + 1 <= 8) ? 2 * c + 1 : 8] : (f32x4){0.f, 0.f, 0.f, 0.f};
;             u32x4 pw; pw.x = pk2(pa[0], pa[1]); pw.y = pk2(pa[2], pa[3]); pw.z = pk2(pb[0], pb[1]); pw.w = pk2(pb[2], pb[3]);
;             const bf16x8 bfrag = __builtin_bit_cast(bf16x8, pw);
; #pragma unroll
;             for (int dt = 0; dt < 4; ++dt) { const LAS bf16_t* vr = Vt + (16 * dt + fr) * VP + 4 * fq;
;                 const u32x2 lo = *(const LAS u32x2*)(vr + KOFF(jtA)), hi = *(const LAS u32x2*)(vr + KOFF(jtB)); const u32x4 av = {lo.x, lo.y, hi.x, hi.y};
;                 o[dt] = __builtin_amdgcn_mfma_f32_16x16x32_bf16(__builtin_bit_cast(bf16x8, av), bfrag, o[dt], 0, 0, 0); } }
	v_max_f32_e32 v60, v60, v60
	v_max_f32_e32 v52, v52, v60
	ds_bpermute_b32 v60, v18, v52
	s_waitcnt lgkmcnt(0)
	v_max_f32_e32 v60, v60, v60
	v_max_f32_e32 v52, v52, v60
	v_sub_f32_e32 v60, v64, v52
	v_exp_f32_e32 v60, v60
	v_sub_f32_e32 v61, v65, v52
	v_exp_f32_e32 v61, v61
	v_sub_f32_e32 v54, v54, v52
	v_exp_f32_e32 v62, v54
	v_sub_f32_e32 v55, v55, v52
	v_exp_f32_e32 v55, v55
	v_sub_f32_e32 v56, v56, v52
	v_add_f32_e32 v54, 0, v60
	v_exp_f32_e32 v56, v56
	v_sub_f32_e32 v57, v57, v52
	v_add_f32_e32 v54, v61, v54
	v_exp_f32_e32 v57, v57
	v_sub_f32_e32 v58, v58, v52
	v_add_f32_e32 v54, v62, v54
	v_exp_f32_e32 v63, v58
	v_sub_f32_e32 v58, v59, v52
	v_add_f32_e32 v54, v55, v54
	v_exp_f32_e32 v64, v58
	v_sub_f32_e32 v58, v66, v52
	v_add_f32_e32 v54, v56, v54
	v_exp_f32_e32 v89, v58
	v_sub_f32_e32 v58, v67, v52
	v_add_f32_e32 v54, v57, v54
	v_exp_f32_e32 v90, v58
	v_sub_f32_e32 v58, v68, v52
	v_add_f32_e32 v54, v63, v54
	v_exp_f32_e32 v91, v58
	v_sub_f32_e32 v58, v69, v52
	v_add_f32_e32 v54, v64, v54
	v_exp_f32_e32 v92, v58
	v_sub_f32_e32 v58, v70, v52
	v_add_f32_e32 v54, v89, v54
	v_exp_f32_e32 v93, v58
	v_sub_f32_e32 v58, v71, v52
	v_add_f32_e32 v54, v90, v54
	v_exp_f32_e32 v94, v58
	v_sub_f32_e32 v58, v72, v52
	v_add_f32_e32 v54, v91, v54
	v_exp_f32_e32 v95, v58
	v_sub_f32_e32 v58, v73, v52
	v_add_f32_e32 v54, v92, v54
	v_exp_f32_e32 v96, v58
	v_sub_f32_e32 v58, v74, v52
	v_add_f32_e32 v54, v93, v54
	v_exp_f32_e32 v97, v58
	v_sub_f32_e32 v58, v75, v52
	v_add_f32_e32 v54, v94, v54
	v_exp_f32_e32 v98, v58
	v_sub_f32_e32 v58, v76, v52
	v_add_f32_e32 v54, v95, v54
	v_exp_f32_e32 v99, v58
	v_sub_f32_e32 v58, v77, v52
	v_add_f32_e32 v54, v96, v54
	v_exp_f32_e32 v100, v58
	v_sub_f32_e32 v58, v78, v52
	v_add_f32_e32 v54, v97, v54
	v_exp_f32_e32 v101, v58
	v_sub_f32_e32 v58, v79, v52
	v_add_f32_e32 v54, v98, v54
	v_exp_f32_e32 v102, v58
	v_sub_f32_e32 v58, v80, v52
	v_add_f32_e32 v54, v99, v54
	v_exp_f32_e32 v103, v58
	v_sub_f32_e32 v58, v81, v52
	v_add_f32_e32 v54, v100, v54
	v_exp_f32_e32 v104, v58
	v_sub_f32_e32 v58, v82, v52
	v_add_f32_e32 v54, v101, v54
	v_exp_f32_e32 v105, v58
	v_sub_f32_e32 v58, v83, v52
	v_add_f32_e32 v54, v102, v54
	v_exp_f32_e32 v106, v58
	v_sub_f32_e32 v58, v84, v52
	v_add_f32_e32 v54, v103, v54
	v_exp_f32_e32 v107, v58
	v_add_f32_e32 v54, v104, v54
	v_sub_f32_e32 v70, v85, v52
	v_add_f32_e32 v54, v105, v54
	v_exp_f32_e32 v108, v70
	v_add_f32_e32 v54, v106, v54
	v_cvt_pk_bf16_f32 v55, v62, v55
	v_add_u32_e32 v62, s26, v19
	v_add_f32_e32 v74, v107, v54
	v_cvt_pk_bf16_f32 v54, v60, v61
	v_add_u32_e32 v65, s2, v20
	ds_read_b64 v[58:59], v62 offset:55296
	ds_read_b64 v[60:61], v65 offset:55296
	v_add_u32_e32 v71, s26, v21
	s_lshl_b32 s26, s42, 8
	v_add_u32_e32 v72, s2, v22
	s_and_b64 s[2:3], s[88:89], exec
	v_cvt_pk_bf16_f32 v56, v56, v57
	v_cvt_pk_bf16_f32 v57, v63, v64
	ds_read_b64 v[64:65], v65 offset:63744
	ds_read_b64 v[62:63], v62 offset:63744
	v_add_f32_e32 v109, v108, v74
	v_sub_f32_e32 v74, v86, v52
	s_cselect_b32 s2, s46, s40
	ds_read_b64 v[66:67], v71 offset:16896
	ds_read_b64 v[68:69], v72 offset:16896
	ds_read_b64 v[72:73], v72 offset:25344
	ds_read_b64 v[70:71], v71 offset:25344
	v_exp_f32_e32 v86, v74
	v_sub_f32_e32 v74, v87, v52
	s_lshl_b32 s2, s2, 8
	v_add_u32_e32 v78, s26, v23
	v_exp_f32_e32 v87, v74
	v_add_u32_e32 v79, s2, v24
	ds_read_b64 v[74:75], v78 offset:55296
	ds_read_b64 v[76:77], v79 offset:55296
	s_waitcnt lgkmcnt(8)
	v_mfma_f32_16x16x32_bf16 v[58:61], v[58:61], v[54:57], 0
	ds_read_b64 v[80:81], v79 offset:63744
	ds_read_b64 v[78:79], v78 offset:63744
	v_sub_f32_e32 v88, v88, v52
	v_exp_f32_e32 v88, v88
	s_waitcnt lgkmcnt(8)
	v_mfma_f32_16x16x32_bf16 v[62:65], v[62:65], v[54:57], 0
	v_sub_f32_e32 v17, v17, v52
	v_exp_f32_e32 v17, v17
	v_sub_f32_e32 v53, v53, v52
	s_waitcnt lgkmcnt(6)
	v_mfma_f32_16x16x32_bf16 v[66:69], v[66:69], v[54:57], 0
	v_exp_f32_e32 v53, v53
	v_sub_f32_e32 v1, v1, v52
	v_exp_f32_e32 v1, v1
	s_waitcnt lgkmcnt(4)
	v_mfma_f32_16x16x32_bf16 v[54:57], v[70:73], v[54:57], 0
	v_cvt_pk_bf16_f32 v70, v89, v90
	v_cvt_pk_bf16_f32 v71, v91, v92
	v_cvt_pk_bf16_f32 v72, v93, v94
	v_cvt_pk_bf16_f32 v73, v95, v96
	v_add_u32_e32 v89, s26, v25
	v_add_u32_e32 v90, s2, v26
	ds_read_b64 v[82:83], v89 offset:16896
	ds_read_b64 v[84:85], v90 offset:16896
	s_waitcnt lgkmcnt(4)
	v_mfma_f32_16x16x32_bf16 v[58:61], v[74:77], v[70:73], v[58:61]
	ds_read_b64 v[76:77], v90 offset:25344
	ds_read_b64 v[74:75], v89 offset:25344
	s_lshl_b32 s26, s47, 8
	s_and_b64 s[2:3], s[90:91], exec
	s_waitcnt lgkmcnt(4)
	v_mfma_f32_16x16x32_bf16 v[62:65], v[78:81], v[70:73], v[62:65]
	v_add_f32_e32 v78, v86, v109
	v_add_f32_e32 v78, v87, v78
	s_cselect_b32 s2, s46, s40
	v_add_f32_e32 v89, v88, v78
	s_lshl_b32 s2, s2, 8
	v_add_u32_e32 v78, s26, v27
	s_waitcnt lgkmcnt(0)
	v_mfma_f32_16x16x32_bf16 v[54:57], v[74:77], v[70:73], v[54:57]
	v_add_u32_e32 v79, s2, v28
	ds_read_b64 v[74:75], v78 offset:55296
	ds_read_b64 v[76:77], v79 offset:55296
	ds_read_b64 v[80:81], v79 offset:63744
	ds_read_b64 v[78:79], v78 offset:63744
	v_mfma_f32_16x16x32_bf16 v[66:69], v[82:85], v[70:73], v[66:69]
	v_cvt_pk_bf16_f32 v70, v97, v98
	v_cvt_pk_bf16_f32 v71, v99, v100
	v_cvt_pk_bf16_f32 v72, v101, v102
	v_cvt_pk_bf16_f32 v73, v103, v104
	v_add_u32_e32 v90, s26, v29
	v_add_u32_e32 v91, s2, v32
	ds_read_b64 v[82:83], v90 offset:16896
	ds_read_b64 v[84:85], v91 offset:16896
	s_waitcnt lgkmcnt(4)
; #define LAS __attribute__((address_space(3)))
; __device__ __forceinline__ unsigned pk2(float lo, float hi) { const f32x2 v = {lo, hi}; return __builtin_bit_cast(unsigned, __builtin_convertvector(v, bf16x2_hw)); }
;     ...
;         l += __shfl_xor(l, 16); l += __shfl_xor(l, 32);
;         f32x4 o[4];
; #pragma unroll
;         for (int dt = 0; dt < 4; ++dt) o[dt] = (f32x4){0.f, 0.f, 0.f, 0.f};
; #pragma unroll
;         for (int c = 0; c < 5; ++c) { const int jtA = w + 2 * c; int jtB = w + 2 * c + 1; jtB = jtB > 15 ? 15 : jtB;
;             const f32x4 pa = sc[2 * c]; const f32x4 pb = (2 * c + 1 <= 8) ? sc[(2 * c + 1 <= 8) ? 2 * c + 1 : 8] : (f32x4){0.f, 0.f, 0.f, 0.f};
;             u32x4 pw; pw.x = pk2(pa[0], pa[1]); pw.y = pk2(pa[2], pa[3]); pw.z = pk2(pb[0], pb[1]); pw.w = pk2(pb[2], pb[3]);
;             const bf16x8 bfrag = __builtin_bit_cast(bf16x8, pw);
; #pragma unroll
;             for (int dt = 0; dt < 4; ++dt) { const LAS bf16_t* vr = Vt + (16 * dt + fr) * VP + 4 * fq;
;                 const u32x2 lo = *(const LAS u32x2*)(vr + KOFF(jtA)), hi = *(const LAS u32x2*)(vr + KOFF(jtB)); const u32x4 av = {lo.x, lo.y, hi.x, hi.y};
;                 o[dt] = __builtin_amdgcn_mfma_f32_16x16x32_bf16(__builtin_bit_cast(bf16x8, av), bfrag, o[dt], 0, 0, 0); } }
;         const float il = 1.0f / l; const int tq = tb + (128 * n + iq) * r;
;         bf16_t* op = (dry ? proj + (size_t)NT * NMAIN + (size_t)(tq & 63) * NMAIN : proj + (size_t)tq * NMAIN) + C_AQ + h * 64 + 4 * fq;
; #pragma unroll
;         for (int dt = 0; dt < 4; ++dt) { u32x2 wv; wv.x = pk2(o[dt][0] * il, o[dt][1] * il); wv.y = pk2(o[dt][2] * il, o[dt][3] * il); *(u32x2*)(op + 16 * dt) = wv; }
;         if (fq == 0) lse[((size_t)g * NT + tq) * 4 + hg] = mx * 0.6931471805599453f + __logf(l);
	v_mfma_f32_16x16x32_bf16 v[58:61], v[74:77], v[70:73], v[58:61]
	ds_read_b64 v[76:77], v91 offset:25344
	ds_read_b64 v[74:75], v90 offset:25344
	s_lshl_b32 s25, s25, 8
	s_and_b64 s[2:3], s[92:93], exec
	s_waitcnt lgkmcnt(4)
	v_mfma_f32_16x16x32_bf16 v[62:65], v[78:81], v[70:73], v[62:65]
	v_add_f32_e32 v78, v17, v89
	s_cselect_b32 s2, s46, s40
	v_add_f32_e32 v89, v53, v78
	s_lshl_b32 s2, s2, 8
	v_add_u32_e32 v78, s25, v33
	s_waitcnt lgkmcnt(0)
	v_mfma_f32_16x16x32_bf16 v[54:57], v[74:77], v[70:73], v[54:57]
	v_add_u32_e32 v79, s2, v34
	ds_read_b64 v[74:75], v78 offset:55296
	ds_read_b64 v[76:77], v79 offset:55296
	v_sub_f32_e32 v2, v2, v52
	v_mfma_f32_16x16x32_bf16 v[66:69], v[82:85], v[70:73], v[66:69]
	v_cvt_pk_bf16_f32 v73, v88, v17
	v_add_u32_e32 v17, s25, v35
	v_exp_f32_e32 v2, v2
	v_cvt_pk_bf16_f32 v72, v86, v87
	ds_read_b64 v[80:81], v79 offset:63744
	ds_read_b64 v[78:79], v78 offset:63744
	v_add_u32_e32 v86, s2, v36
	ds_read_b64 v[82:83], v17 offset:16896
	ds_read_b64 v[84:85], v86 offset:16896
	v_sub_f32_e32 v0, v0, v52
	v_exp_f32_e32 v88, v0
	v_cvt_pk_bf16_f32 v70, v105, v106
	v_cvt_pk_bf16_f32 v71, v107, v108
	s_lshl_b32 s24, s24, 8
	s_and_b64 s[2:3], s[94:95], exec
	s_waitcnt lgkmcnt(4)
	v_mfma_f32_16x16x32_bf16 v[58:61], v[74:77], v[70:73], v[58:61]
	v_add_f32_e32 v74, v1, v89
	v_add_f32_e32 v87, v2, v74
	s_cselect_b32 s2, s46, s40
	ds_read_b64 v[76:77], v86 offset:25344
	ds_read_b64 v[74:75], v17 offset:25344
	s_waitcnt lgkmcnt(2)
	v_mfma_f32_16x16x32_bf16 v[66:69], v[82:85], v[70:73], v[66:69]
	s_lshl_b32 s2, s2, 8
	v_add_u32_e32 v17, s24, v19
	v_add_f32_e32 v83, v88, v87
	v_mfma_f32_16x16x32_bf16 v[62:65], v[78:81], v[70:73], v[62:65]
	v_add_u32_e32 v82, s2, v37
	ds_read_b64 v[78:79], v17 offset:55296
	ds_read_b64 v[80:81], v82 offset:55296
	ds_bpermute_b32 v84, v7, v83
	v_cvt_pk_bf16_f32 v0, v53, v1
	v_cvt_pk_bf16_f32 v1, v2, v88
	v_mov_b32_e32 v2, v3
	s_waitcnt lgkmcnt(3)
	v_mfma_f32_16x16x32_bf16 v[54:57], v[74:77], v[70:73], v[54:57]
	ds_read_b64 v[72:73], v82 offset:63744
	ds_read_b64 v[70:71], v17 offset:63744
	v_add_u32_e32 v17, s24, v21
	v_add_u32_e32 v53, s2, v38
	s_waitcnt lgkmcnt(3)
	v_mfma_f32_16x16x32_bf16 v[58:61], v[78:81], v[0:3], v[58:61]
	s_waitcnt lgkmcnt(2)
	v_add_f32_e32 v78, v83, v84
	ds_bpermute_b32 v79, v18, v78
	ds_read_b64 v[74:75], v17 offset:16896
	ds_read_b64 v[76:77], v53 offset:16896
	s_waitcnt lgkmcnt(3)
	v_mfma_f32_16x16x32_bf16 v[62:65], v[70:73], v[0:3], v[62:65]
	ds_read_b64 v[72:73], v53 offset:25344
	ds_read_b64 v[70:71], v17 offset:25344
	s_waitcnt lgkmcnt(4)
	v_add_f32_e32 v53, v78, v79
	v_div_scale_f32 v17, s[2:3], v53, v53, 1.0
	s_waitcnt lgkmcnt(2)
	v_mfma_f32_16x16x32_bf16 v[66:69], v[74:77], v[0:3], v[66:69]
	v_rcp_f32_e32 v74, v17
	s_waitcnt lgkmcnt(0)
	v_mfma_f32_16x16x32_bf16 v[54:57], v[70:73], v[0:3], v[54:57]
	v_fma_f32 v0, -v17, v74, 1.0
	v_fmac_f32_e32 v74, v0, v74
	v_div_scale_f32 v0, vcc, 1.0, v53, 1.0
	v_mul_f32_e32 v1, v0, v74
	v_fma_f32 v2, -v17, v1, v0
	v_fmac_f32_e32 v1, v2, v74
	v_fma_f32 v0, -v17, v1, v0
	v_div_fmas_f32 v0, v0, v74, v1
	v_div_fixup_f32 v2, v0, v53, 1.0
	v_add_u32_e32 v0, s45, v5
	v_lshlrev_b32_e32 v0, s97, v0
	v_add_u32_e32 v0, s44, v0
	v_mov_b64_e32 v[70:71], s[48:49]
	v_mad_i64_i32 v[70:71], s[2:3], v0, s35, v[70:71]
	v_lshl_add_u64 v[70:71], s[0:1], 1, v[70:71]
	v_mov_b32_e32 v17, v3
	v_lshl_add_u64 v[70:71], v[70:71], 0, v[16:17]
	v_pk_mul_f32 v[58:59], v[2:3], v[58:59] op_sel_hi:[0,1]
	v_pk_mul_f32 v[60:61], v[2:3], v[60:61] op_sel_hi:[0,1]
	v_cvt_pk_bf16_f32 v58, v58, v59
	v_cvt_pk_bf16_f32 v59, v60, v61
	v_add_co_u32_e32 v60, vcc, s29, v70
	s_mov_b64 s[0:1], 0x1800
	s_nop 0
	v_addc_co_u32_e32 v61, vcc, 0, v71, vcc
	global_store_dwordx2 v[60:61], v[58:59], off offset:2048
	v_pk_mul_f32 v[58:59], v[2:3], v[62:63] op_sel_hi:[0,1]
	v_pk_mul_f32 v[60:61], v[2:3], v[64:65] op_sel_hi:[0,1]
	v_lshl_add_u64 v[72:73], v[70:71], 0, s[0:1]
	v_cvt_pk_bf16_f32 v58, v58, v59
	v_cvt_pk_bf16_f32 v59, v60, v61
	global_store_dwordx2 v[72:73], v[58:59], off offset:32
	v_pk_mul_f32 v[58:59], v[2:3], v[66:67] op_sel_hi:[0,1]
	v_pk_mul_f32 v[60:61], v[2:3], v[68:69] op_sel_hi:[0,1]
	v_pk_mul_f32 v[54:55], v[2:3], v[54:55] op_sel_hi:[0,1]
	v_pk_mul_f32 v[56:57], v[2:3], v[56:57] op_sel_hi:[0,1]
	v_cvt_pk_bf16_f32 v58, v58, v59
	v_cvt_pk_bf16_f32 v59, v60, v61
	v_cvt_pk_bf16_f32 v54, v54, v55
	v_cvt_pk_bf16_f32 v55, v56, v57
	global_store_dwordx2 v[72:73], v[58:59], off offset:64
	global_store_dwordx2 v[72:73], v[54:55], off offset:96
	s_and_saveexec_b64 s[0:1], s[6:7]
	s_cbranch_execz .LBB0_331
	v_cmp_gt_f32_e32 vcc, s31, v53
	s_ashr_i32 s97, s96, 31
	s_lshl_b64 s[2:3], s[96:97], 18
	v_cndmask_b32_e64 v1, 0, 32, vcc
	v_ldexp_f32 v1, v53, v1
	v_log_f32_e32 v2, v1
	s_add_u32 s2, s5, s2
	v_ashrrev_i32_e32 v1, 31, v0
	v_cndmask_b32_e32 v17, 0, v30, vcc
	v_mul_f32_e32 v53, 0x3f317217, v2
	v_fma_f32 v53, v2, s36, -v53
	v_fmac_f32_e32 v53, 0x3377d1cf, v2
	v_fmac_f32_e32 v53, 0x3f317217, v2
	v_cmp_lt_f32_e64 vcc, |v2|, s37
	s_addc_u32 s3, s33, s3
	v_lshl_add_u64 v[0:1], v[0:1], 4, s[2:3]
	v_cndmask_b32_e32 v2, v2, v53, vcc
	s_lshr_b32 s2, s38, 3
	v_sub_f32_e32 v2, v2, v17
	s_and_b32 s38, s2, 12
	v_fmac_f32_e32 v2, 0x3f317218, v52
	v_lshl_add_u64 v[0:1], v[0:1], 0, s[38:39]
	global_store_dword v[0:1], v2, off
	s_branch .LBB0_331
